# tail-interleaved half epilogue + relaxed first two waits of the next unit (vmcnt 24) so the remaining epilogue stores need not retire first
# speedup vs baseline: 1.0093x; 1.0044x over previous
.LBB0_105:
	v_mov_b32_e32 v165, v27
	v_lshl_add_u64 v[58:59], s[86:87], 0, v[164:165]
	v_mov_b32_e32 v161, v27
	v_lshl_add_u64 v[84:85], s[86:87], 0, v[160:161]
	s_add_i32 m0, s17, 0x18000
	v_lshl_add_u64 v[58:59], v[58:59], 0, s[82:83]
	v_readlane_b32 s26, v251, 55
	v_mov_b32_e32 v167, v27
	s_waitcnt vmcnt(2)
	s_barrier
	global_load_lds_dwordx4 v[58:59], off
	v_lshl_add_u64 v[58:59], v[84:85], 0, s[82:83]
	s_add_i32 m0, s17, 0x1a000
	v_readlane_b32 s27, v251, 56
	s_add_i32 s22, s17, 0x8000
	v_mov_b32_e32 v163, v27
	global_load_lds_dwordx4 v[58:59], off
	v_lshl_add_u64 v[58:59], s[26:27], 0, v[166:167]
	s_mov_b32 m0, s22
	s_add_i32 s80, s17, 0xa000
	global_load_lds_dwordx4 v[58:59], off
	v_lshl_add_u64 v[58:59], s[26:27], 0, v[162:163]
	s_mov_b32 m0, s80
	s_and_b32 s1, s1, 3
	global_load_lds_dwordx4 v[58:59], off
	s_add_i32 m0, s17, 0x1c000
	v_lshl_add_u64 v[58:59], s[52:53], 0, v[164:165]
	global_load_lds_dwordx4 v[58:59], off
	v_lshl_add_u64 v[58:59], s[52:53], 0, v[160:161]
	s_add_i32 m0, s17, 0x1e000
	v_mul_lo_u32 v26, v26, s7
	global_load_lds_dwordx4 v[58:59], off
	v_bfe_u32 v59, v37, 4, 2
	v_and_b32_e32 v58, 15, v37
	v_lshlrev_b32_e32 v185, 4, v59
	v_lshlrev_b32_e32 v37, 2, v37
	v_lshl_or_b32 v184, s11, 6, v58
	v_lshl_or_b32 v58, v58, 6, v185
	s_lshl_b32 s11, s11, 13
	v_and_b32_e32 v37, 32, v37
	v_bitop3_b32 v84, v58, s11, v37 bitop3:0xde
	s_lshl_b32 s11, s1, 12
	v_bitop3_b32 v186, v58, s11, v37 bitop3:0xde
	s_cmpk_lt_u32 s0, 0x100
	v_lshrrev_b32_e32 v37, 1, v56
	v_mul_lo_u32 v58, v39, s7
	s_mov_b32 s11, 0x2c000
	s_cselect_b64 s[60:61], -1, 0
	v_cmp_eq_u32_e64 s[38:39], 0, v59
	s_lshl_b32 s26, s1, 1
	v_lshl_or_b32 v187, s1, 6, v185
	v_mad_u64_u32 v[58:59], s[0:1], v37, s11, v[58:59]
	v_and_b32_e32 v37, 1, v56
	v_lshl_or_b32 v37, v37, 6, v58
	v_lshl_add_u32 v176, v57, 1, v37
	v_lshrrev_b32_e32 v37, 1, v36
	v_mad_u64_u32 v[56:57], s[0:1], v37, s11, v[26:27]
	s_waitcnt vmcnt(6)
	v_and_b32_e32 v26, 1, v36
	v_readlane_b32 s0, v251, 36
	v_lshl_or_b32 v26, v26, 6, v56
	s_mov_b32 s94, s0
	v_readlane_b32 s0, v251, 34
	v_readlane_b32 s78, v251, 37
	s_mov_b32 s81, 0
	s_orn2_b32 s26, s26, 47
	v_mov_b32_e32 v177, v27
	v_lshl_add_u32 v178, v38, 1, v26
	v_mov_b32_e32 v179, v27
	v_add_u32_e32 v188, 0, v84
	v_readlane_b32 s31, v251, 35
	s_mov_b32 s30, s0
	s_mov_b64 s[76:77], s[86:87]
	v_readlane_b32 s79, v251, 38
	s_and_b32 s98, s94, -8
	s_lshl_b32 s98, s98, 14
	s_add_u32 s98, s57, s98
	s_addc_u32 s99, s15, 0
	v_lshlrev_b32_e32 v132, 6, v0
	v_add_u32_e32 v133, 0x8000, v132
	v_add_u32_e32 v134, 0x10000, v132
	v_add_u32_e32 v135, 0x18000, v132
	global_load_dwordx4 v[100:103], v132, s[98:99]
	global_load_dwordx4 v[104:107], v132, s[98:99] offset:16
	global_load_dwordx4 v[108:111], v132, s[98:99] offset:32
	global_load_dwordx4 v[112:115], v132, s[98:99] offset:48
	global_load_dwordx4 v[116:119], v133, s[98:99]
	global_load_dwordx4 v[120:123], v133, s[98:99] offset:16
	global_load_dwordx4 v[124:127], v133, s[98:99] offset:32
	global_load_dwordx4 v[128:131], v133, s[98:99] offset:48
	global_load_dwordx4 v[190:193], v134, s[98:99]
	global_load_dwordx4 v[194:197], v134, s[98:99] offset:16
	global_load_dwordx4 v[198:201], v134, s[98:99] offset:32
	global_load_dwordx4 v[202:205], v134, s[98:99] offset:48
	global_load_dwordx4 v[206:209], v135, s[98:99]
	global_load_dwordx4 v[210:213], v135, s[98:99] offset:16
	global_load_dwordx4 v[214:217], v135, s[98:99] offset:32
	global_load_dwordx4 v[218:221], v135, s[98:99] offset:48
	v_lshlrev_b32_e32 v140, 2, v0
	v_add_u32_e32 v140, 0x20000, v140
	s_waitcnt vmcnt(0)
	v_add_f32_e32 v101, v101, v100
	v_add_f32_e32 v102, v102, v103
	v_add_f32_e32 v100, v101, v102
	v_add_f32_e32 v105, v105, v104
	v_add_f32_e32 v106, v106, v107
	v_add_f32_e32 v104, v105, v106
	v_add_f32_e32 v109, v109, v108
	v_add_f32_e32 v110, v110, v111
	v_add_f32_e32 v108, v109, v110
	v_add_f32_e32 v113, v113, v112
	v_add_f32_e32 v114, v114, v115
	v_add_f32_e32 v112, v113, v114
	v_add_f32_e32 v100, v100, v104
	v_add_f32_e32 v108, v108, v112
	v_add_f32_e32 v136, v100, v108
	v_add_f32_e32 v117, v117, v116
	v_add_f32_e32 v118, v118, v119
	v_add_f32_e32 v116, v117, v118
	v_add_f32_e32 v121, v121, v120
	v_add_f32_e32 v122, v122, v123
	v_add_f32_e32 v120, v121, v122
	v_add_f32_e32 v125, v125, v124
	v_add_f32_e32 v126, v126, v127
	v_add_f32_e32 v124, v125, v126
	v_add_f32_e32 v129, v129, v128
	v_add_f32_e32 v130, v130, v131
	v_add_f32_e32 v128, v129, v130
	v_add_f32_e32 v116, v116, v120
	v_add_f32_e32 v124, v124, v128
	v_add_f32_e32 v137, v116, v124
	v_add_f32_e32 v191, v191, v190
	v_add_f32_e32 v192, v192, v193
	v_add_f32_e32 v190, v191, v192
	v_add_f32_e32 v195, v195, v194
	v_add_f32_e32 v196, v196, v197
	v_add_f32_e32 v194, v195, v196
	v_add_f32_e32 v199, v199, v198
	v_add_f32_e32 v200, v200, v201
	v_add_f32_e32 v198, v199, v200
	v_add_f32_e32 v203, v203, v202
	v_add_f32_e32 v204, v204, v205
	v_add_f32_e32 v202, v203, v204
	v_add_f32_e32 v190, v190, v194
	v_add_f32_e32 v198, v198, v202
	v_add_f32_e32 v138, v190, v198
	v_add_f32_e32 v207, v207, v206
	v_add_f32_e32 v208, v208, v209
	v_add_f32_e32 v206, v207, v208
	v_add_f32_e32 v211, v211, v210
	v_add_f32_e32 v212, v212, v213
	v_add_f32_e32 v210, v211, v212
	v_add_f32_e32 v215, v215, v214
	v_add_f32_e32 v216, v216, v217
	v_add_f32_e32 v214, v215, v216
	v_add_f32_e32 v219, v219, v218
	v_add_f32_e32 v220, v220, v221
	v_add_f32_e32 v218, v219, v220
	v_add_f32_e32 v206, v206, v210
	v_add_f32_e32 v214, v214, v218
	v_add_f32_e32 v139, v206, v214
	v_fmamk_f32 v136, v136, 0x3a800000, v222
	v_fmamk_f32 v137, v137, 0x3a800000, v222
	v_fmamk_f32 v138, v138, 0x3a800000, v222
	v_fmamk_f32 v139, v139, 0x3a800000, v222
	v_rsq_f32_e32 v136, v136
	v_rsq_f32_e32 v137, v137
	v_rsq_f32_e32 v138, v138
	v_rsq_f32_e32 v139, v139
	s_nop 0
	ds_write_b32 v140, v136
	ds_write_b32 v140, v137 offset:2048
	ds_write_b32 v140, v138 offset:4096
	ds_write_b32 v140, v139 offset:6144
	s_waitcnt lgkmcnt(0)
	s_barrier
	s_mov_b32 s98, 0
	s_branch .LBB0_108
